# P2: half of the workgroups (bit 3 of blockIdx) run their dilated-branch items before their windowed items so compute-bound and memory-bound items overlap across the chip
# speedup vs baseline: 1.0053x; 1.0053x over previous
; __device__ __forceinline__ Item decode(int k, int na0, int nA, int nb0) {
;     Item I; int tok0;
;     if (k < nA) { const int ia = na0 + k; I.isA = 1; I.hs = ia / (TT / 128); tok0 = (ia % (TT / 128)) * 128; I.dil = 1; }
;     else { const int ib = nb0 + (k - nA); I.hs = ib / (TT / 256); I.isA = 0; const int gi = I.hs >> 2; tok0 = (ib % (TT / 256)) * 256; I.dil = gi == 0 ? 1 : (gi == 1 ? 4 : 16); }
;     int L;
;     if (tok0 < TP) { L = 2048; I.seq0 = (tok0 / 2048) * 2048; } else { L = 8192; I.seq0 = TP + ((tok0 - TP) / 8192) * 8192; }
;     I.res = 0; I.j0 = tok0 - I.seq0; I.Lr = L; I.Lre = L; I.pair = 0;
;     ...
;     const int na0 = (int)((long)bx * NITEM_A / G), nA = (int)((long)(bx + 1) * NITEM_A / G) - na0;
;     const int nb0 = (int)((long)bx * NITEM_B / G), nB = (int)((long)(bx + 1) * NITEM_B / G) - nb0;
;     const int nloc = nA + nB, r0 = tid >> 3, ch = tid & 7;
;     v4u pk[6], pv[6];
;     ...
;     if (nloc <= 0) return;
;     Item cur = decode(0, na0, nA, nb0), nxt = cur;
.LBB0_146:
	s_sub_i32 s3, s4, s12
	s_add_u32 s14, s20, 0x7800000
	s_addc_u32 s15, s21, 0
	s_sub_i32 s13, s8, s44
	s_add_i32 s13, s13, s3
	s_mov_b32 s32, 0
	s_bitcmp1_b32 s2, 3
	s_cbranch_scc0 .Lmy_noswap
	s_mov_b32 s3, 0
	s_sub_i32 s12, s12, 15
	s_mov_b32 s32, 15
.Lmy_noswap:
	s_cmp_gt_i32 s13, 0
	s_cbranch_scc0 .LBB0_255
	s_cmp_lt_i32 s3, 1
	s_cselect_b64 s[4:5], -1, 0
	s_mov_b32 s70, 1
	s_and_b64 vcc, exec, s[4:5]
	s_cbranch_vccnz .LBB0_153
	s_mul_hi_i32 s0, s12, 0x66666667
	s_lshr_b32 s1, s0, 31
	s_ashr_i32 s0, s0, 8
	s_add_i32 s46, s0, s1
	s_mul_i32 s0, s46, 0x280
	s_sub_i32 s0, s12, s0
	s_lshl_b32 s0, s0, 7
	s_mov_b32 s45, 1
	s_cbranch_execz .LBB0_154
	s_branch .LBB0_155

; __device__ __forceinline__ Item decode(int k, int na0, int nA, int nb0) {
;     Item I; int tok0;
;     if (k < nA) { const int ia = na0 + k; I.isA = 1; I.hs = ia / (TT / 128); tok0 = (ia % (TT / 128)) * 128; I.dil = 1; }
;     else { const int ib = nb0 + (k - nA); I.hs = ib / (TT / 256); I.isA = 0; const int gi = I.hs >> 2; tok0 = (ib % (TT / 256)) * 256; I.dil = gi == 0 ? 1 : (gi == 1 ? 4 : 16); }
;     ...
;         const bool more = (k + 1 < nloc);
;         if (more) { nxt = decode(k + 1, na0, nA, nb0); ATT_ISSUE(nxt); }
.LBB0_209:
	s_andn2_b64 vcc, exec, s[58:59]
	s_mov_b32 s69, s97
	s_mov_b32 s86, s99
	s_mov_b32 s85, s98
	s_mov_b32 s68, s45
	s_mov_b32 s87, s92
	s_mov_b32 s67, s46
	s_mov_b32 s0, s65
	s_cbranch_vccnz .LBB0_238
	s_sub_i32 s0, s84, s32
	s_cmp_ge_u32 s0, 5
	s_cselect_b64 s[58:59], -1, 0
	s_mov_b64 s[60:61], -1
	s_and_b64 vcc, exec, s[58:59]
	s_cbranch_vccz .LBB0_220
	s_sub_i32 s0, s84, s3
	s_add_i32 s0, s0, s44
	s_mul_hi_i32 s1, s0, 0x66666667
	s_lshr_b32 s60, s1, 31
	s_ashr_i32 s1, s1, 7
	s_add_i32 s67, s1, s60
	s_mul_i32 s1, s67, 0x140
	s_sub_i32 s0, s0, s1
	s_lshl_b32 s0, s0, 8
	s_and_b32 s1, s67, -4
	s_cmp_eq_u32 s1, 4
	s_cselect_b32 s1, 4, 16
	s_cmp_gt_u32 s67, 3
	s_cselect_b32 s68, s1, 1
	s_mov_b32 s70, 0
	s_cbranch_execz .LBB0_221
